# G1 and G3 K-loop back edge rotated: counter update, exit test and loop branch moved in front of the closing barrier (barrier becomes the loop head)
# baseline (speedup 1.0000x reference)
; #define PG8_STAGE(bufoff, gbase, voff) do { _Pragma("unroll") for (int _i = 0; _i < 2; ++_i) \
;         __builtin_amdgcn_global_load_lds((const unsigned*)((const char*)(gbase) + (voff)[_i]), (PG8_LAS unsigned*)(lds + (bufoff) + ldsw + _i * 8192), 16, 0, 0); } while (0)
; #define PG8_LDA(dst, b, h) do { _Pragma("unroll") for (int m = 0; m < 4; ++m) _Pragma("unroll") for (int k = 0; k < 2; ++k) dst[m][k] = *(const PG8_LAS bf16x8*)(lds + PG8_SA(b, h) + aoff + m * 2048 + k * 1024); } while (0)
; #define PG8_LDB(dst, b, h) do { _Pragma("unroll") for (int n = 0; n < 2; ++n) _Pragma("unroll") for (int k = 0; k < 2; ++k) dst[n][k] = *(const PG8_LAS bf16x8*)(lds + PG8_SB(b, h) + boff + n * 2048 + k * 1024); } while (0)
; template <class Epi, class Sched, bool ALIGN_EPI = false, bool SP2 = false>
; __device__ __forceinline__ void gemm_phase(PG8_LAS unsigned char* lds, const Gemm g, const Sched& S, const Epi& E) {
;     ...
;     f32x4 acc[2][2][4][2];
; #pragma unroll
;     for (int a = 0; a < 2; ++a)
; #pragma unroll
;         for (int b = 0; b < 2; ++b)
; #pragma unroll
;             for (int m = 0; m < 4; ++m)
; #pragma unroll
;                 for (int n = 0; n < 2; ++n) acc[a][b][m][n] = (f32x4){0.f, 0.f, 0.f, 0.f};
;     bf16x8 At[4][2], B0[2][2], B1[2][2];
;     const char* cA = (const char*)g.A + (size_t)cur.pm * tstep; const char* cB = (const char*)g.Bt + (size_t)cur.pn * tstep;
;     ...
;         const bool has_next = S.next(ui + 1, nxt);
;         const char* nA = has_next ? (const char*)g.A + (size_t)nxt.pm * tstep : cA; const char* nB = has_next ? (const char*)g.Bt + (size_t)nxt.pn * tstep : cB;
;         for (int t = 0; t < nt; t += 2) {
;             const bool last = (t == nt - 2);
;             const char* a1 = cA + (size_t)(t + 1) * kstep;
;             const char* a2 = last ? nA : cA + (size_t)(t + 2) * kstep; const char* b2 = last ? nB : cB + (size_t)(t + 2) * kstep;
;             const char* a3 = a2 + kstep; const char* b3 = b2 + kstep;
;             if (last && has_next) S.a_ready(nxt);
;             if constexpr (Epi::MID) { if (t == nt / 2) E.mid(acc, cur, wr, wc, fr, fq); }
;             if constexpr (SP2) {
;             PG8_LDB(B0, 0, 0); PG8_LDB(B1, 0, 1); PG8_SCHED; PG8_LDA(At, 0, 0); PG8_STAGE(PG8_SA(1, 1), a1 + hstep, voffA);
;             PG8_WAIT_V(8); PG8_WAIT_L(0); PG8_BAR; PG8_MMA(0, 0, At, B0); PG8_MMA(0, 1, At, B1); PG8_BAR; PG8_SCHED;
.LBB0_37:
	s_ashr_i32 s55, s54, 31
	s_lshl_b64 s[2:3], s[54:55], 20
	s_add_u32 s56, s46, s2
	s_addc_u32 s57, s47, s3
	s_and_b64 s[2:3], s[40:41], exec
	s_cselect_b32 s2, s57, s63
	s_cselect_b32 s3, s56, s62
	s_ashr_i32 s53, s52, 31
	s_lshl_b64 s[58:59], s[52:53], 20
	s_add_u32 s58, s66, s58
	s_addc_u32 s59, s67, s59
	s_mov_b32 s95, s65
	s_and_b64 s[64:65], s[40:41], exec
	s_cselect_b32 s53, s59, s61
	s_cselect_b32 s55, s58, s60
	s_add_u32 s79, s60, 0x100
	s_addc_u32 s82, s61, 0
	s_add_u32 s60, s62, 0x80080
	v_mov_b32_e32 v2, 0
	s_addc_u32 s61, s63, 0
	s_mov_b32 s83, -2
	v_mov_b32_e32 v3, v2
	v_mov_b32_e32 v4, v2
	v_mov_b32_e32 v5, v2
	v_mov_b32_e32 v6, v2
	s_waitcnt lgkmcnt(0)
	v_mov_b32_e32 v7, v2
	v_mov_b32_e32 v8, v2
	v_mov_b32_e32 v9, v2
	v_mov_b32_e32 v18, v2
	v_mov_b32_e32 v19, v2
	v_mov_b32_e32 v20, v2
	v_mov_b32_e32 v21, v2
	v_mov_b32_e32 v22, v2
	v_mov_b32_e32 v23, v2
	v_mov_b32_e32 v24, v2
	v_mov_b32_e32 v25, v2
	v_mov_b32_e32 v34, v2
	v_mov_b32_e32 v35, v2
	v_mov_b32_e32 v36, v2
	v_mov_b32_e32 v37, v2
	v_mov_b32_e32 v38, v2
	v_mov_b32_e32 v39, v2
	v_mov_b32_e32 v40, v2
	v_mov_b32_e32 v41, v2
	v_mov_b32_e32 v50, v2
	v_mov_b32_e32 v51, v2
	v_mov_b32_e32 v52, v2
	v_mov_b32_e32 v53, v2
	v_mov_b32_e32 v54, v2
	v_mov_b32_e32 v55, v2
	v_mov_b32_e32 v56, v2
	v_mov_b32_e32 v57, v2
	v_mov_b32_e32 v10, v2
	v_mov_b32_e32 v11, v2
	v_mov_b32_e32 v12, v2
	v_mov_b32_e32 v13, v2
	v_mov_b32_e32 v14, v2
	v_mov_b32_e32 v15, v2
	v_mov_b32_e32 v16, v2
	v_mov_b32_e32 v17, v2
	v_mov_b32_e32 v26, v2
	v_mov_b32_e32 v27, v2
	v_mov_b32_e32 v28, v2
	v_mov_b32_e32 v29, v2
	v_mov_b32_e32 v30, v2
	v_mov_b32_e32 v31, v2
	v_mov_b32_e32 v32, v2
	v_mov_b32_e32 v33, v2
	v_mov_b32_e32 v42, v2
	v_mov_b32_e32 v43, v2
	v_mov_b32_e32 v44, v2
	v_mov_b32_e32 v45, v2
	v_mov_b32_e32 v46, v2
	v_mov_b32_e32 v47, v2
	v_mov_b32_e32 v48, v2
	v_mov_b32_e32 v49, v2
	v_mov_b32_e32 v58, v2
	v_mov_b32_e32 v59, v2
	v_mov_b32_e32 v60, v2
	v_mov_b32_e32 v61, v2
	v_mov_b32_e32 v62, v2
	v_mov_b32_e32 v63, v2
	v_mov_b32_e32 v64, v2
	v_mov_b32_e32 v65, v2
	v_mov_b32_e32 v66, v2
	v_mov_b32_e32 v67, v2
	v_mov_b32_e32 v68, v2
	v_mov_b32_e32 v69, v2
	v_mov_b32_e32 v70, v2
	v_mov_b32_e32 v71, v2
	v_mov_b32_e32 v72, v2
	v_mov_b32_e32 v73, v2
	v_mov_b32_e32 v82, v2
	v_mov_b32_e32 v83, v2
	v_mov_b32_e32 v84, v2
	v_mov_b32_e32 v85, v2
	v_mov_b32_e32 v86, v2
	v_mov_b32_e32 v87, v2
	v_mov_b32_e32 v88, v2
	v_mov_b32_e32 v89, v2
	v_mov_b32_e32 v98, v2
	v_mov_b32_e32 v99, v2
	v_mov_b32_e32 v100, v2
	v_mov_b32_e32 v101, v2
	v_mov_b32_e32 v102, v2
	v_mov_b32_e32 v103, v2
	v_mov_b32_e32 v104, v2
	v_mov_b32_e32 v105, v2
	v_mov_b32_e32 v114, v2
	v_mov_b32_e32 v115, v2
	v_mov_b32_e32 v116, v2
	v_mov_b32_e32 v117, v2
	v_mov_b32_e32 v118, v2
	v_mov_b32_e32 v119, v2
	v_mov_b32_e32 v120, v2
	v_mov_b32_e32 v121, v2
	v_mov_b32_e32 v74, v2
	v_mov_b32_e32 v75, v2
	v_mov_b32_e32 v76, v2
	v_mov_b32_e32 v77, v2
	v_mov_b32_e32 v78, v2
	v_mov_b32_e32 v79, v2
	v_mov_b32_e32 v80, v2
	v_mov_b32_e32 v81, v2
	v_mov_b32_e32 v90, v2
	v_mov_b32_e32 v91, v2
	v_mov_b32_e32 v92, v2
	v_mov_b32_e32 v93, v2
	v_mov_b32_e32 v94, v2
	v_mov_b32_e32 v95, v2
	v_mov_b32_e32 v96, v2
	v_mov_b32_e32 v97, v2
	v_mov_b32_e32 v106, v2
	v_mov_b32_e32 v107, v2
	v_mov_b32_e32 v108, v2
	v_mov_b32_e32 v109, v2
	v_mov_b32_e32 v110, v2
	v_mov_b32_e32 v111, v2
	v_mov_b32_e32 v112, v2
	v_mov_b32_e32 v113, v2
	v_mov_b32_e32 v122, v2
	v_mov_b32_e32 v123, v2
	v_mov_b32_e32 v124, v2
	v_mov_b32_e32 v125, v2
	v_mov_b32_e32 v126, v2
	v_mov_b32_e32 v127, v2
	v_mov_b32_e32 v128, v2
	v_mov_b32_e32 v129, v2
	s_branch .LBB0_38
.Lg3_head_bar:
	s_barrier
.LBB0_38:
	s_add_u32 s62, s60, 0xfff80080
	s_addc_u32 s63, s61, -1
	s_add_i32 s86, 0, 0x10000
	s_cmp_eq_u32 s83, 28
	s_cselect_b32 s65, s2, s63
	s_cselect_b32 s64, s3, s62
	v_add_u32_e32 v142, s86, v156
	s_cselect_b32 s63, s53, s82
	s_cselect_b32 s62, s55, s79
	s_add_i32 s88, 0, 0x14000
	ds_read_b128 v[152:155], v142
	ds_read_b128 v[160:163], v142 offset:1024
	ds_read_b128 v[164:167], v142 offset:2048
	ds_read_b128 v[182:185], v142 offset:3072
	v_add_u32_e32 v142, s88, v156
	ds_read_b128 v[186:189], v142
	ds_read_b128 v[190:193], v142 offset:1024
	ds_read_b128 v[194:197], v142 offset:2048
	ds_read_b128 v[198:201], v142 offset:3072
	v_lshl_add_u64 v[142:143], s[60:61], 0, v[150:151]
	s_add_i32 m0, s69, 0xc000
	ds_read_b128 v[202:205], v158
	ds_read_b128 v[206:209], v158 offset:1024
	ds_read_b128 v[214:217], v158 offset:2048
	ds_read_b128 v[218:221], v158 offset:3072
	ds_read_b128 v[222:225], v158 offset:4096
	ds_read_b128 v[226:229], v158 offset:5120
	ds_read_b128 v[230:233], v158 offset:6144
	ds_read_b128 v[234:237], v158 offset:7168
	global_load_lds_dwordx4 v[142:143], off
	v_lshl_add_u64 v[142:143], s[60:61], 0, v[136:137]
	s_add_i32 m0, s69, 0xe000
	s_nop 0
	global_load_lds_dwordx4 v[142:143], off
	s_waitcnt vmcnt(8)
	s_waitcnt lgkmcnt(0)
	s_setprio 1
	s_barrier
; #define PG8_STAGE(bufoff, gbase, voff) do { _Pragma("unroll") for (int _i = 0; _i < 2; ++_i) \
;         __builtin_amdgcn_global_load_lds((const unsigned*)((const char*)(gbase) + (voff)[_i]), (PG8_LAS unsigned*)(lds + (bufoff) + ldsw + _i * 8192), 16, 0, 0); } while (0)
; #define PG8_LDA(dst, b, h) do { _Pragma("unroll") for (int m = 0; m < 4; ++m) _Pragma("unroll") for (int k = 0; k < 2; ++k) dst[m][k] = *(const PG8_LAS bf16x8*)(lds + PG8_SA(b, h) + aoff + m * 2048 + k * 1024); } while (0)
; #define PG8_MMA(ai, bj, At, Bt) do { __builtin_amdgcn_s_setprio(1); _Pragma("unroll") for (int m = 0; m < 4; ++m) _Pragma("unroll") for (int n = 0; n < 2; ++n) _Pragma("unroll") for (int k = 0; k < 2; ++k) \
;         acc[ai][bj][m][n] = __builtin_amdgcn_mfma_f32_16x16x32_bf16(Bt[n][k], At[m][k], acc[ai][bj][m][n], 0, 0, 0); __builtin_amdgcn_s_setprio(0); } while (0)
; #define PG8_WAIT_V(n) asm volatile("s_waitcnt vmcnt(" #n ")" ::: "memory")
; #define PG8_WAIT_L(n) asm volatile("s_waitcnt lgkmcnt(" #n ")" ::: "memory")
; #define PG8_BAR __builtin_amdgcn_s_barrier()
; #define PG8_SCHED __builtin_amdgcn_sched_barrier(0)
; template <class Epi, class Sched, bool ALIGN_EPI = false, bool SP2 = false>
; __device__ __forceinline__ void gemm_phase(PG8_LAS unsigned char* lds, const Gemm g, const Sched& S, const Epi& E) {
;     ...
;             PG8_WAIT_V(8); PG8_WAIT_L(0); PG8_BAR; PG8_MMA(0, 0, At, B0); PG8_MMA(0, 1, At, B1); PG8_BAR; PG8_SCHED;
;             PG8_LDA(At, 0, 1); PG8_STAGE(PG8_SB(0, 0), b2, voffB); PG8_STAGE(PG8_SB(0, 1), b2 + hstep, voffB); PG8_STAGE(PG8_SA(0, 0), a2, voffA);
;             PG8_WAIT_V(8); PG8_WAIT_L(0); PG8_BAR; PG8_MMA(1, 0, At, B0); PG8_MMA(1, 1, At, B1); PG8_BAR; PG8_SCHED;
	v_mfma_f32_16x16x32_bf16 v[126:129], v[152:155], v[202:205], v[126:129]
	v_mfma_f32_16x16x32_bf16 v[122:125], v[164:167], v[202:205], v[122:125]
	v_mfma_f32_16x16x32_bf16 v[110:113], v[152:155], v[214:217], v[110:113]
	v_mfma_f32_16x16x32_bf16 v[106:109], v[164:167], v[214:217], v[106:109]
	v_mfma_f32_16x16x32_bf16 v[94:97], v[152:155], v[222:225], v[94:97]
	v_mfma_f32_16x16x32_bf16 v[90:93], v[164:167], v[222:225], v[90:93]
	v_mfma_f32_16x16x32_bf16 v[78:81], v[152:155], v[230:233], v[78:81]
	v_mfma_f32_16x16x32_bf16 v[74:77], v[164:167], v[230:233], v[74:77]
	v_mfma_f32_16x16x32_bf16 v[126:129], v[160:163], v[206:209], v[126:129]
	v_mfma_f32_16x16x32_bf16 v[122:125], v[182:185], v[206:209], v[122:125]
	v_mfma_f32_16x16x32_bf16 v[110:113], v[160:163], v[218:221], v[110:113]
	v_mfma_f32_16x16x32_bf16 v[106:109], v[182:185], v[218:221], v[106:109]
	v_mfma_f32_16x16x32_bf16 v[94:97], v[160:163], v[226:229], v[94:97]
	v_mfma_f32_16x16x32_bf16 v[90:93], v[182:185], v[226:229], v[90:93]
	v_mfma_f32_16x16x32_bf16 v[78:81], v[160:163], v[234:237], v[78:81]
	v_mfma_f32_16x16x32_bf16 v[74:77], v[182:185], v[234:237], v[74:77]
	s_setprio 0
	s_setprio 1
	v_mfma_f32_16x16x32_bf16 v[118:121], v[186:189], v[202:205], v[118:121]
	v_mfma_f32_16x16x32_bf16 v[114:117], v[194:197], v[202:205], v[114:117]
	v_mfma_f32_16x16x32_bf16 v[102:105], v[186:189], v[214:217], v[102:105]
	v_mfma_f32_16x16x32_bf16 v[98:101], v[194:197], v[214:217], v[98:101]
	v_mfma_f32_16x16x32_bf16 v[86:89], v[186:189], v[222:225], v[86:89]
	v_mfma_f32_16x16x32_bf16 v[82:85], v[194:197], v[222:225], v[82:85]
	v_mfma_f32_16x16x32_bf16 v[70:73], v[186:189], v[230:233], v[70:73]
	v_mfma_f32_16x16x32_bf16 v[66:69], v[194:197], v[230:233], v[66:69]
	v_mfma_f32_16x16x32_bf16 v[118:121], v[190:193], v[206:209], v[118:121]
	v_mfma_f32_16x16x32_bf16 v[114:117], v[198:201], v[206:209], v[114:117]
	v_mfma_f32_16x16x32_bf16 v[102:105], v[190:193], v[218:221], v[102:105]
	v_mfma_f32_16x16x32_bf16 v[98:101], v[198:201], v[218:221], v[98:101]
	v_mfma_f32_16x16x32_bf16 v[86:89], v[190:193], v[226:229], v[86:89]
	v_mfma_f32_16x16x32_bf16 v[82:85], v[198:201], v[226:229], v[82:85]
	v_mfma_f32_16x16x32_bf16 v[70:73], v[190:193], v[234:237], v[70:73]
	v_mfma_f32_16x16x32_bf16 v[66:69], v[198:201], v[234:237], v[66:69]
	s_setprio 0
	s_barrier
	s_add_i32 s86, s86, s68
	v_lshl_add_u64 v[142:143], s[62:63], 0, v[0:1]
	s_mov_b32 m0, s86
	ds_read_b128 v[202:205], v158 offset:16384
	ds_read_b128 v[206:209], v158 offset:17408
	ds_read_b128 v[214:217], v158 offset:18432
	ds_read_b128 v[218:221], v158 offset:19456
	ds_read_b128 v[222:225], v158 offset:20480
	ds_read_b128 v[226:229], v158 offset:21504
	ds_read_b128 v[230:233], v158 offset:22528
	ds_read_b128 v[234:237], v158 offset:23552
	global_load_lds_dwordx4 v[142:143], off
	s_add_i32 m0, s86, 0x2000
	s_add_u32 s86, s62, 0x80000
	v_lshl_add_u64 v[144:145], s[62:63], 0, v[130:131]
	s_addc_u32 s87, s63, 0
	s_add_i32 s88, s88, s68
	global_load_lds_dwordx4 v[144:145], off
	v_lshl_add_u64 v[168:169], s[86:87], 0, v[0:1]
	s_mov_b32 m0, s88
	v_lshl_add_u64 v[238:239], s[64:65], 0, v[132:133]
	global_load_lds_dwordx4 v[168:169], off
	v_lshl_add_u64 v[168:169], s[86:87], 0, v[130:131]
	s_add_i32 m0, s88, 0x2000
	s_nop 0
	global_load_lds_dwordx4 v[168:169], off
	v_lshl_add_u64 v[168:169], s[64:65], 0, v[134:135]
	s_mov_b32 m0, s69
	s_nop 0
	global_load_lds_dwordx4 v[168:169], off
	s_mov_b32 m0, s70
	s_nop 0
	global_load_lds_dwordx4 v[238:239], off
	s_waitcnt vmcnt(8)
	s_waitcnt lgkmcnt(0)
	s_setprio 1
	s_barrier
	v_mfma_f32_16x16x32_bf16 v[62:65], v[152:155], v[202:205], v[62:65]
	v_mfma_f32_16x16x32_bf16 v[58:61], v[164:167], v[202:205], v[58:61]
	v_mfma_f32_16x16x32_bf16 v[46:49], v[152:155], v[214:217], v[46:49]
	v_mfma_f32_16x16x32_bf16 v[42:45], v[164:167], v[214:217], v[42:45]
	v_mfma_f32_16x16x32_bf16 v[30:33], v[152:155], v[222:225], v[30:33]
	v_mfma_f32_16x16x32_bf16 v[26:29], v[164:167], v[222:225], v[26:29]
	v_mfma_f32_16x16x32_bf16 v[14:17], v[152:155], v[230:233], v[14:17]
	v_mfma_f32_16x16x32_bf16 v[10:13], v[164:167], v[230:233], v[10:13]
	v_mfma_f32_16x16x32_bf16 v[62:65], v[160:163], v[206:209], v[62:65]
	v_mfma_f32_16x16x32_bf16 v[58:61], v[182:185], v[206:209], v[58:61]
	v_mfma_f32_16x16x32_bf16 v[46:49], v[160:163], v[218:221], v[46:49]
	v_mfma_f32_16x16x32_bf16 v[42:45], v[182:185], v[218:221], v[42:45]
	v_mfma_f32_16x16x32_bf16 v[30:33], v[160:163], v[226:229], v[30:33]
	v_mfma_f32_16x16x32_bf16 v[26:29], v[182:185], v[226:229], v[26:29]
	v_mfma_f32_16x16x32_bf16 v[14:17], v[160:163], v[234:237], v[14:17]
	v_mfma_f32_16x16x32_bf16 v[10:13], v[182:185], v[234:237], v[10:13]
	s_setprio 0
	s_setprio 1
	v_mfma_f32_16x16x32_bf16 v[54:57], v[186:189], v[202:205], v[54:57]
	v_mfma_f32_16x16x32_bf16 v[50:53], v[194:197], v[202:205], v[50:53]
	v_mfma_f32_16x16x32_bf16 v[38:41], v[186:189], v[214:217], v[38:41]
	v_mfma_f32_16x16x32_bf16 v[34:37], v[194:197], v[214:217], v[34:37]
	v_mfma_f32_16x16x32_bf16 v[22:25], v[186:189], v[222:225], v[22:25]
	v_mfma_f32_16x16x32_bf16 v[18:21], v[194:197], v[222:225], v[18:21]
	v_mfma_f32_16x16x32_bf16 v[6:9], v[186:189], v[230:233], v[6:9]
	v_mfma_f32_16x16x32_bf16 v[2:5], v[194:197], v[230:233], v[2:5]
	v_mfma_f32_16x16x32_bf16 v[54:57], v[190:193], v[206:209], v[54:57]
	v_mfma_f32_16x16x32_bf16 v[50:53], v[198:201], v[206:209], v[50:53]
	v_mfma_f32_16x16x32_bf16 v[38:41], v[190:193], v[218:221], v[38:41]
	v_mfma_f32_16x16x32_bf16 v[34:37], v[198:201], v[218:221], v[34:37]
	v_mfma_f32_16x16x32_bf16 v[22:25], v[190:193], v[226:229], v[22:25]
	v_mfma_f32_16x16x32_bf16 v[18:21], v[198:201], v[226:229], v[18:21]
	v_mfma_f32_16x16x32_bf16 v[6:9], v[190:193], v[234:237], v[6:9]
	v_mfma_f32_16x16x32_bf16 v[2:5], v[198:201], v[234:237], v[2:5]
	s_setprio 0
	s_barrier
; #define PG8_STAGE(bufoff, gbase, voff) do { _Pragma("unroll") for (int _i = 0; _i < 2; ++_i) \
;         __builtin_amdgcn_global_load_lds((const unsigned*)((const char*)(gbase) + (voff)[_i]), (PG8_LAS unsigned*)(lds + (bufoff) + ldsw + _i * 8192), 16, 0, 0); } while (0)
; #define PG8_LDA(dst, b, h) do { _Pragma("unroll") for (int m = 0; m < 4; ++m) _Pragma("unroll") for (int k = 0; k < 2; ++k) dst[m][k] = *(const PG8_LAS bf16x8*)(lds + PG8_SA(b, h) + aoff + m * 2048 + k * 1024); } while (0)
; #define PG8_LDB(dst, b, h) do { _Pragma("unroll") for (int n = 0; n < 2; ++n) _Pragma("unroll") for (int k = 0; k < 2; ++k) dst[n][k] = *(const PG8_LAS bf16x8*)(lds + PG8_SB(b, h) + boff + n * 2048 + k * 1024); } while (0)
; #define PG8_MMA(ai, bj, At, Bt) do { __builtin_amdgcn_s_setprio(1); _Pragma("unroll") for (int m = 0; m < 4; ++m) _Pragma("unroll") for (int n = 0; n < 2; ++n) _Pragma("unroll") for (int k = 0; k < 2; ++k) \
;         acc[ai][bj][m][n] = __builtin_amdgcn_mfma_f32_16x16x32_bf16(Bt[n][k], At[m][k], acc[ai][bj][m][n], 0, 0, 0); __builtin_amdgcn_s_setprio(0); } while (0)
; #define PG8_WAIT_V(n) asm volatile("s_waitcnt vmcnt(" #n ")" ::: "memory")
; #define PG8_WAIT_L(n) asm volatile("s_waitcnt lgkmcnt(" #n ")" ::: "memory")
; #define PG8_BAR __builtin_amdgcn_s_barrier()
; #define PG8_SCHED __builtin_amdgcn_sched_barrier(0)
; template <class Epi, class Sched, bool ALIGN_EPI = false, bool SP2 = false>
; __device__ __forceinline__ void gemm_phase(PG8_LAS unsigned char* lds, const Gemm g, const Sched& S, const Epi& E) {
;     ...
;             PG8_LDB(B0, 1, 0); PG8_LDB(B1, 1, 1); PG8_SCHED; PG8_LDA(At, 1, 0); PG8_STAGE(PG8_SA(0, 1), a2 + hstep, voffA);
;             PG8_WAIT_V(8); PG8_WAIT_L(0); PG8_BAR; PG8_MMA(0, 0, At, B0); PG8_MMA(0, 1, At, B1); PG8_BAR; PG8_SCHED;
	s_add_i32 s86, 0, 0x18000
	v_add_u32_e32 v159, s86, v156
	s_add_i32 s87, 0, 0x1c000
	ds_read_b128 v[152:155], v159
	ds_read_b128 v[160:163], v159 offset:1024
	ds_read_b128 v[164:167], v159 offset:2048
	ds_read_b128 v[182:185], v159 offset:3072
	v_add_u32_e32 v159, s87, v156
	ds_read_b128 v[186:189], v159
	ds_read_b128 v[190:193], v159 offset:1024
	ds_read_b128 v[194:197], v159 offset:2048
	ds_read_b128 v[198:201], v159 offset:3072
	s_add_u32 s64, s64, 0x80000
	s_addc_u32 s65, s65, 0
	s_mov_b32 m0, s71
	v_lshl_add_u64 v[240:241], s[64:65], 0, v[134:135]
	ds_read_b128 v[202:205], v158 offset:32768
	ds_read_b128 v[206:209], v158 offset:33792
	ds_read_b128 v[214:217], v158 offset:34816
	ds_read_b128 v[218:221], v158 offset:35840
	ds_read_b128 v[222:225], v158 offset:36864
	ds_read_b128 v[226:229], v158 offset:37888
	ds_read_b128 v[230:233], v158 offset:38912
	ds_read_b128 v[234:237], v158 offset:39936
	global_load_lds_dwordx4 v[240:241], off
	v_lshl_add_u64 v[240:241], s[64:65], 0, v[132:133]
	s_mov_b32 m0, s72
	s_nop 0
	global_load_lds_dwordx4 v[240:241], off
	s_waitcnt vmcnt(8)
	s_waitcnt lgkmcnt(0)
	s_setprio 1
	s_barrier
	v_mfma_f32_16x16x32_bf16 v[126:129], v[152:155], v[202:205], v[126:129]
	v_mfma_f32_16x16x32_bf16 v[122:125], v[164:167], v[202:205], v[122:125]
	v_mfma_f32_16x16x32_bf16 v[110:113], v[152:155], v[214:217], v[110:113]
	v_mfma_f32_16x16x32_bf16 v[106:109], v[164:167], v[214:217], v[106:109]
	v_mfma_f32_16x16x32_bf16 v[94:97], v[152:155], v[222:225], v[94:97]
	v_mfma_f32_16x16x32_bf16 v[90:93], v[164:167], v[222:225], v[90:93]
	v_mfma_f32_16x16x32_bf16 v[78:81], v[152:155], v[230:233], v[78:81]
	v_mfma_f32_16x16x32_bf16 v[74:77], v[164:167], v[230:233], v[74:77]
	v_mfma_f32_16x16x32_bf16 v[126:129], v[160:163], v[206:209], v[126:129]
	v_mfma_f32_16x16x32_bf16 v[122:125], v[182:185], v[206:209], v[122:125]
	v_mfma_f32_16x16x32_bf16 v[110:113], v[160:163], v[218:221], v[110:113]
	v_mfma_f32_16x16x32_bf16 v[106:109], v[182:185], v[218:221], v[106:109]
	v_mfma_f32_16x16x32_bf16 v[94:97], v[160:163], v[226:229], v[94:97]
	v_mfma_f32_16x16x32_bf16 v[90:93], v[182:185], v[226:229], v[90:93]
	v_mfma_f32_16x16x32_bf16 v[78:81], v[160:163], v[234:237], v[78:81]
	v_mfma_f32_16x16x32_bf16 v[74:77], v[182:185], v[234:237], v[74:77]
	s_setprio 0
	s_setprio 1
	v_mfma_f32_16x16x32_bf16 v[118:121], v[186:189], v[202:205], v[118:121]
	v_mfma_f32_16x16x32_bf16 v[114:117], v[194:197], v[202:205], v[114:117]
	v_mfma_f32_16x16x32_bf16 v[102:105], v[186:189], v[214:217], v[102:105]
	v_mfma_f32_16x16x32_bf16 v[98:101], v[194:197], v[214:217], v[98:101]
	v_mfma_f32_16x16x32_bf16 v[86:89], v[186:189], v[222:225], v[86:89]
	v_mfma_f32_16x16x32_bf16 v[82:85], v[194:197], v[222:225], v[82:85]
	v_mfma_f32_16x16x32_bf16 v[70:73], v[186:189], v[230:233], v[70:73]
	v_mfma_f32_16x16x32_bf16 v[66:69], v[194:197], v[230:233], v[66:69]
	v_mfma_f32_16x16x32_bf16 v[118:121], v[190:193], v[206:209], v[118:121]
	v_mfma_f32_16x16x32_bf16 v[114:117], v[198:201], v[206:209], v[114:117]
	v_mfma_f32_16x16x32_bf16 v[102:105], v[190:193], v[218:221], v[102:105]
	v_mfma_f32_16x16x32_bf16 v[98:101], v[198:201], v[218:221], v[98:101]
	v_mfma_f32_16x16x32_bf16 v[86:89], v[190:193], v[226:229], v[86:89]
	v_mfma_f32_16x16x32_bf16 v[82:85], v[198:201], v[226:229], v[82:85]
	v_mfma_f32_16x16x32_bf16 v[70:73], v[190:193], v[234:237], v[70:73]
	v_mfma_f32_16x16x32_bf16 v[66:69], v[198:201], v[234:237], v[66:69]
	s_setprio 0
	s_barrier
; #define PG8_STAGE(bufoff, gbase, voff) do { _Pragma("unroll") for (int _i = 0; _i < 2; ++_i) \
;         __builtin_amdgcn_global_load_lds((const unsigned*)((const char*)(gbase) + (voff)[_i]), (PG8_LAS unsigned*)(lds + (bufoff) + ldsw + _i * 8192), 16, 0, 0); } while (0)
; #define PG8_LDA(dst, b, h) do { _Pragma("unroll") for (int m = 0; m < 4; ++m) _Pragma("unroll") for (int k = 0; k < 2; ++k) dst[m][k] = *(const PG8_LAS bf16x8*)(lds + PG8_SA(b, h) + aoff + m * 2048 + k * 1024); } while (0)
; #define PG8_MMA(ai, bj, At, Bt) do { __builtin_amdgcn_s_setprio(1); _Pragma("unroll") for (int m = 0; m < 4; ++m) _Pragma("unroll") for (int n = 0; n < 2; ++n) _Pragma("unroll") for (int k = 0; k < 2; ++k) \
;         acc[ai][bj][m][n] = __builtin_amdgcn_mfma_f32_16x16x32_bf16(Bt[n][k], At[m][k], acc[ai][bj][m][n], 0, 0, 0); __builtin_amdgcn_s_setprio(0); } while (0)
; #define PG8_WAIT_V(n) asm volatile("s_waitcnt vmcnt(" #n ")" ::: "memory")
; #define PG8_WAIT_L(n) asm volatile("s_waitcnt lgkmcnt(" #n ")" ::: "memory")
; #define PG8_BAR __builtin_amdgcn_s_barrier()
; #define PG8_SCHED __builtin_amdgcn_sched_barrier(0)
; template <class Epi, class Sched, bool ALIGN_EPI = false, bool SP2 = false>
; __device__ __forceinline__ void gemm_phase(PG8_LAS unsigned char* lds, const Gemm g, const Sched& S, const Epi& E) {
;     ...
;         for (int t = 0; t < nt; t += 2) {
;     ...
;             PG8_LDA(At, 1, 1); PG8_STAGE(PG8_SB(1, 0), b3, voffB); PG8_STAGE(PG8_SB(1, 1), b3 + hstep, voffB); PG8_STAGE(PG8_SA(1, 0), a3, voffA);
;             PG8_WAIT_V(8); PG8_WAIT_L(0); PG8_BAR; PG8_MMA(1, 0, At, B0); PG8_MMA(1, 1, At, B1); PG8_BAR; PG8_SCHED;
	s_add_i32 s64, s86, s68
	v_lshl_add_u64 v[142:143], v[142:143], 0, s[34:35]
	s_mov_b32 m0, s64
	ds_read_b128 v[202:205], v158 offset:49152
	ds_read_b128 v[206:209], v158 offset:50176
	ds_read_b128 v[214:217], v158 offset:51200
	ds_read_b128 v[218:221], v158 offset:52224
	ds_read_b128 v[222:225], v158 offset:53248
	ds_read_b128 v[226:229], v158 offset:54272
	ds_read_b128 v[230:233], v158 offset:55296
	ds_read_b128 v[234:237], v158 offset:56320
	global_load_lds_dwordx4 v[142:143], off
	s_add_i32 m0, s64, 0x2000
	s_add_u32 s62, s62, 0x80080
	v_lshl_add_u64 v[142:143], v[144:145], 0, s[34:35]
	s_addc_u32 s63, s63, 0
	s_add_i32 s64, s87, s68
	global_load_lds_dwordx4 v[142:143], off
	v_lshl_add_u64 v[142:143], s[62:63], 0, v[0:1]
	s_mov_b32 m0, s64
	s_nop 0
	global_load_lds_dwordx4 v[142:143], off
	v_lshl_add_u64 v[142:143], s[62:63], 0, v[130:131]
	s_add_i32 m0, s64, 0x2000
	s_nop 0
	global_load_lds_dwordx4 v[142:143], off
	v_lshl_add_u64 v[142:143], v[168:169], 0, s[34:35]
	s_mov_b32 m0, s74
	s_nop 0
	global_load_lds_dwordx4 v[142:143], off
	v_lshl_add_u64 v[142:143], v[238:239], 0, s[34:35]
	s_mov_b32 m0, s75
	s_nop 0
	global_load_lds_dwordx4 v[142:143], off
	s_waitcnt vmcnt(8)
	s_waitcnt lgkmcnt(0)
	s_setprio 1
	s_barrier
	v_mfma_f32_16x16x32_bf16 v[62:65], v[152:155], v[202:205], v[62:65]
	v_mfma_f32_16x16x32_bf16 v[58:61], v[164:167], v[202:205], v[58:61]
	v_mfma_f32_16x16x32_bf16 v[46:49], v[152:155], v[214:217], v[46:49]
	v_mfma_f32_16x16x32_bf16 v[42:45], v[164:167], v[214:217], v[42:45]
	v_mfma_f32_16x16x32_bf16 v[30:33], v[152:155], v[222:225], v[30:33]
	v_mfma_f32_16x16x32_bf16 v[26:29], v[164:167], v[222:225], v[26:29]
	v_mfma_f32_16x16x32_bf16 v[14:17], v[152:155], v[230:233], v[14:17]
	v_mfma_f32_16x16x32_bf16 v[10:13], v[164:167], v[230:233], v[10:13]
	v_mfma_f32_16x16x32_bf16 v[62:65], v[160:163], v[206:209], v[62:65]
	v_mfma_f32_16x16x32_bf16 v[58:61], v[182:185], v[206:209], v[58:61]
	v_mfma_f32_16x16x32_bf16 v[46:49], v[160:163], v[218:221], v[46:49]
	v_mfma_f32_16x16x32_bf16 v[42:45], v[182:185], v[218:221], v[42:45]
	v_mfma_f32_16x16x32_bf16 v[30:33], v[160:163], v[226:229], v[30:33]
	v_mfma_f32_16x16x32_bf16 v[26:29], v[182:185], v[226:229], v[26:29]
	v_mfma_f32_16x16x32_bf16 v[14:17], v[160:163], v[234:237], v[14:17]
	v_mfma_f32_16x16x32_bf16 v[10:13], v[182:185], v[234:237], v[10:13]
	s_setprio 0
	s_setprio 1
	v_mfma_f32_16x16x32_bf16 v[54:57], v[186:189], v[202:205], v[54:57]
	v_mfma_f32_16x16x32_bf16 v[50:53], v[194:197], v[202:205], v[50:53]
	v_mfma_f32_16x16x32_bf16 v[38:41], v[186:189], v[214:217], v[38:41]
	v_mfma_f32_16x16x32_bf16 v[34:37], v[194:197], v[214:217], v[34:37]
	v_mfma_f32_16x16x32_bf16 v[22:25], v[186:189], v[222:225], v[22:25]
	v_mfma_f32_16x16x32_bf16 v[18:21], v[194:197], v[222:225], v[18:21]
	v_mfma_f32_16x16x32_bf16 v[6:9], v[186:189], v[230:233], v[6:9]
	v_mfma_f32_16x16x32_bf16 v[2:5], v[194:197], v[230:233], v[2:5]
	v_mfma_f32_16x16x32_bf16 v[54:57], v[190:193], v[206:209], v[54:57]
	v_mfma_f32_16x16x32_bf16 v[50:53], v[198:201], v[206:209], v[50:53]
	v_mfma_f32_16x16x32_bf16 v[38:41], v[190:193], v[218:221], v[38:41]
	v_mfma_f32_16x16x32_bf16 v[34:37], v[198:201], v[218:221], v[34:37]
	v_mfma_f32_16x16x32_bf16 v[22:25], v[190:193], v[226:229], v[22:25]
	v_mfma_f32_16x16x32_bf16 v[18:21], v[198:201], v[226:229], v[18:21]
	v_mfma_f32_16x16x32_bf16 v[6:9], v[190:193], v[234:237], v[6:9]
	v_mfma_f32_16x16x32_bf16 v[2:5], v[198:201], v[234:237], v[2:5]
	s_setprio 0
	s_add_i32 s83, s83, 2
	s_add_u32 s79, s79, 0x100
	s_addc_u32 s82, s82, 0
	s_add_u32 s60, s60, 0x100
	s_addc_u32 s61, s61, 0
	s_cmp_gt_u32 s83, 29
	s_cbranch_scc0 .Lg3_head_bar
	s_barrier
	s_and_b64 vcc, exec, s[50:51]
	s_cbranch_vccz .LBB0_41
	s_barrier

; template <class Epi, class Sched, bool ALIGN_EPI = false, bool SP2 = false>
; __device__ __forceinline__ void gemm_phase(PG8_LAS unsigned char* lds, const Gemm g, const Sched& S, const Epi& E) {
;     ...
;     f32x4 acc[2][2][4][2];
; #pragma unroll
;     for (int a = 0; a < 2; ++a)
; #pragma unroll
;         for (int b = 0; b < 2; ++b)
; #pragma unroll
;             for (int m = 0; m < 4; ++m)
; #pragma unroll
;                 for (int n = 0; n < 2; ++n) acc[a][b][m][n] = (f32x4){0.f, 0.f, 0.f, 0.f};
;     bf16x8 At[4][2], B0[2][2], B1[2][2];
;     const char* cA = (const char*)g.A + (size_t)cur.pm * tstep; const char* cB = (const char*)g.Bt + (size_t)cur.pn * tstep;
;     ...
;         const char* nA = has_next ? (const char*)g.A + (size_t)nxt.pm * tstep : cA; const char* nB = has_next ? (const char*)g.Bt + (size_t)nxt.pn * tstep : cB;
.LBB0_417:
	s_ashr_i32 s51, s50, 31
	s_lshl_b64 s[2:3], s[50:51], 20
	s_add_u32 s52, s46, s2
	s_addc_u32 s53, s47, s3
	s_and_b64 s[2:3], s[38:39], exec
	s_cselect_b32 s2, s53, s57
	s_cselect_b32 s3, s52, s56
	s_ashr_i32 s49, s48, 31
	s_lshl_b64 s[54:55], s[48:49], 20
	s_add_u32 s54, s60, s54
	s_addc_u32 s55, s61, s55
	s_and_b64 s[58:59], s[38:39], exec
	s_cselect_b32 s49, s55, s41
	s_cselect_b32 s51, s54, s40
	s_add_u32 s72, s40, 0x100
	s_addc_u32 s73, s41, 0
	s_add_u32 s40, s56, 0x80080
	v_mov_b32_e32 v2, 0
	s_addc_u32 s41, s57, 0
	s_mov_b32 s74, -2
	v_mov_b32_e32 v3, v2
	v_mov_b32_e32 v4, v2
	v_mov_b32_e32 v5, v2
	v_mov_b32_e32 v6, v2
	v_mov_b32_e32 v7, v2
	v_mov_b32_e32 v8, v2
	v_mov_b32_e32 v9, v2
	v_mov_b32_e32 v18, v2
	v_mov_b32_e32 v19, v2
	v_mov_b32_e32 v20, v2
	v_mov_b32_e32 v21, v2
	v_mov_b32_e32 v22, v2
	v_mov_b32_e32 v23, v2
	v_mov_b32_e32 v24, v2
	v_mov_b32_e32 v25, v2
	v_mov_b32_e32 v34, v2
	v_mov_b32_e32 v35, v2
	v_mov_b32_e32 v36, v2
	v_mov_b32_e32 v37, v2
	v_mov_b32_e32 v38, v2
	v_mov_b32_e32 v39, v2
	v_mov_b32_e32 v40, v2
	v_mov_b32_e32 v41, v2
	v_mov_b32_e32 v50, v2
	v_mov_b32_e32 v51, v2
	v_mov_b32_e32 v52, v2
	v_mov_b32_e32 v53, v2
	v_mov_b32_e32 v54, v2
	v_mov_b32_e32 v55, v2
	v_mov_b32_e32 v56, v2
	v_mov_b32_e32 v57, v2
	v_mov_b32_e32 v10, v2
	v_mov_b32_e32 v11, v2
	v_mov_b32_e32 v12, v2
	v_mov_b32_e32 v13, v2
	v_mov_b32_e32 v14, v2
	v_mov_b32_e32 v15, v2
	v_mov_b32_e32 v16, v2
	v_mov_b32_e32 v17, v2
	v_mov_b32_e32 v26, v2
	v_mov_b32_e32 v27, v2
	v_mov_b32_e32 v28, v2
	v_mov_b32_e32 v29, v2
	v_mov_b32_e32 v30, v2
	v_mov_b32_e32 v31, v2
	v_mov_b32_e32 v32, v2
	v_mov_b32_e32 v33, v2
	v_mov_b32_e32 v42, v2
	v_mov_b32_e32 v43, v2
	v_mov_b32_e32 v44, v2
	v_mov_b32_e32 v45, v2
	v_mov_b32_e32 v46, v2
	v_mov_b32_e32 v47, v2
	v_mov_b32_e32 v48, v2
	v_mov_b32_e32 v49, v2
	v_mov_b32_e32 v58, v2
	v_mov_b32_e32 v59, v2
	v_mov_b32_e32 v60, v2
	v_mov_b32_e32 v61, v2
	v_mov_b32_e32 v62, v2
	v_mov_b32_e32 v63, v2
	v_mov_b32_e32 v64, v2
	v_mov_b32_e32 v65, v2
	v_mov_b32_e32 v66, v2
	v_mov_b32_e32 v67, v2
	v_mov_b32_e32 v68, v2
	v_mov_b32_e32 v69, v2
	v_mov_b32_e32 v70, v2
	v_mov_b32_e32 v71, v2
	v_mov_b32_e32 v72, v2
	v_mov_b32_e32 v73, v2
	v_mov_b32_e32 v82, v2
	v_mov_b32_e32 v83, v2
	v_mov_b32_e32 v84, v2
	v_mov_b32_e32 v85, v2
	v_mov_b32_e32 v86, v2
	v_mov_b32_e32 v87, v2
	v_mov_b32_e32 v88, v2
	v_mov_b32_e32 v89, v2
	v_mov_b32_e32 v98, v2
	v_mov_b32_e32 v99, v2
	v_mov_b32_e32 v100, v2
	v_mov_b32_e32 v101, v2
	v_mov_b32_e32 v102, v2
	v_mov_b32_e32 v103, v2
	v_mov_b32_e32 v104, v2
	v_mov_b32_e32 v105, v2
	v_mov_b32_e32 v114, v2
	v_mov_b32_e32 v115, v2
	v_mov_b32_e32 v116, v2
	v_mov_b32_e32 v117, v2
	v_mov_b32_e32 v118, v2
	v_mov_b32_e32 v119, v2
	v_mov_b32_e32 v120, v2
	v_mov_b32_e32 v121, v2
	v_mov_b32_e32 v74, v2
	v_mov_b32_e32 v75, v2
	v_mov_b32_e32 v76, v2
	v_mov_b32_e32 v77, v2
	v_mov_b32_e32 v78, v2
	v_mov_b32_e32 v79, v2
	v_mov_b32_e32 v80, v2
	v_mov_b32_e32 v81, v2
	v_mov_b32_e32 v90, v2
	v_mov_b32_e32 v91, v2
	v_mov_b32_e32 v92, v2
	v_mov_b32_e32 v93, v2
	v_mov_b32_e32 v94, v2
	v_mov_b32_e32 v95, v2
	v_mov_b32_e32 v96, v2
	v_mov_b32_e32 v97, v2
	v_mov_b32_e32 v106, v2
	v_mov_b32_e32 v107, v2
	v_mov_b32_e32 v108, v2
	v_mov_b32_e32 v109, v2
	v_mov_b32_e32 v110, v2
	v_mov_b32_e32 v111, v2
	v_mov_b32_e32 v112, v2
	v_mov_b32_e32 v113, v2
	v_mov_b32_e32 v122, v2
	v_mov_b32_e32 v123, v2
	v_mov_b32_e32 v124, v2
	v_mov_b32_e32 v125, v2
	v_mov_b32_e32 v126, v2
	v_mov_b32_e32 v127, v2
	v_mov_b32_e32 v128, v2
	v_mov_b32_e32 v129, v2
	s_branch .LBB0_418

; #define PG8_STAGE(bufoff, gbase, voff) do { _Pragma("unroll") for (int _i = 0; _i < 2; ++_i) \
;         __builtin_amdgcn_global_load_lds((const unsigned*)((const char*)(gbase) + (voff)[_i]), (PG8_LAS unsigned*)(lds + (bufoff) + ldsw + _i * 8192), 16, 0, 0); } while (0)
; #define PG8_LDA(dst, b, h) do { _Pragma("unroll") for (int m = 0; m < 4; ++m) _Pragma("unroll") for (int k = 0; k < 2; ++k) dst[m][k] = *(const PG8_LAS bf16x8*)(lds + PG8_SA(b, h) + aoff + m * 2048 + k * 1024); } while (0)
; #define PG8_LDB(dst, b, h) do { _Pragma("unroll") for (int n = 0; n < 2; ++n) _Pragma("unroll") for (int k = 0; k < 2; ++k) dst[n][k] = *(const PG8_LAS bf16x8*)(lds + PG8_SB(b, h) + boff + n * 2048 + k * 1024); } while (0)
; #define PG8_MMA(ai, bj, At, Bt) do { __builtin_amdgcn_s_setprio(1); _Pragma("unroll") for (int m = 0; m < 4; ++m) _Pragma("unroll") for (int n = 0; n < 2; ++n) _Pragma("unroll") for (int k = 0; k < 2; ++k) \
;         acc[ai][bj][m][n] = __builtin_amdgcn_mfma_f32_16x16x32_bf16(Bt[n][k], At[m][k], acc[ai][bj][m][n], 0, 0, 0); __builtin_amdgcn_s_setprio(0); } while (0)
; #define PG8_WAIT_V(n) asm volatile("s_waitcnt vmcnt(" #n ")" ::: "memory")
; #define PG8_WAIT_L(n) asm volatile("s_waitcnt lgkmcnt(" #n ")" ::: "memory")
; #define PG8_BAR __builtin_amdgcn_s_barrier()
; template <class Epi, class Sched, bool ALIGN_EPI = false, bool SP2 = false>
; __device__ __forceinline__ void gemm_phase(PG8_LAS unsigned char* lds, const Gemm g, const Sched& S, const Epi& E) {
;     ...
;             const bool last = (t == nt - 2);
;             const char* a1 = cA + (size_t)(t + 1) * kstep;
;             const char* a2 = last ? nA : cA + (size_t)(t + 2) * kstep; const char* b2 = last ? nB : cB + (size_t)(t + 2) * kstep;
;             const char* a3 = a2 + kstep; const char* b3 = b2 + kstep;
;             if (last && has_next) S.a_ready(nxt);
;             if constexpr (Epi::MID) { if (t == nt / 2) E.mid(acc, cur, wr, wc, fr, fq); }
;             if constexpr (SP2) {
;             PG8_LDB(B0, 0, 0); PG8_LDB(B1, 0, 1); PG8_SCHED; PG8_LDA(At, 0, 0); PG8_STAGE(PG8_SA(1, 1), a1 + hstep, voffA);
;             PG8_WAIT_V(8); PG8_WAIT_L(0); PG8_BAR; PG8_MMA(0, 0, At, B0); PG8_MMA(0, 1, At, B1); PG8_BAR; PG8_SCHED;
;             PG8_LDA(At, 0, 1); PG8_STAGE(PG8_SB(0, 0), b2, voffB); PG8_STAGE(PG8_SB(0, 1), b2 + hstep, voffB); PG8_STAGE(PG8_SA(0, 0), a2, voffA);
.LBB0_418:
	s_add_u32 s56, s40, 0xfff80080
	s_addc_u32 s57, s41, -1
	s_add_i32 s75, 0, 0x10000
	s_cmp_eq_u32 s74, 28
	s_cselect_b32 s59, s2, s57
	s_cselect_b32 s58, s3, s56
	v_add_u32_e32 v142, s75, v156
	s_cselect_b32 s57, s49, s73
	s_cselect_b32 s56, s51, s72
	s_add_i32 s78, 0, 0x14000
	ds_read_b128 v[152:155], v142
	ds_read_b128 v[160:163], v142 offset:1024
	ds_read_b128 v[164:167], v142 offset:2048
	ds_read_b128 v[182:185], v142 offset:3072
	v_add_u32_e32 v142, s78, v156
	ds_read_b128 v[186:189], v142
	ds_read_b128 v[190:193], v142 offset:1024
	ds_read_b128 v[194:197], v142 offset:2048
	ds_read_b128 v[198:201], v142 offset:3072
	v_lshl_add_u64 v[168:169], s[40:41], 0, v[150:151]
	s_add_i32 m0, s63, 0xc000
	ds_read_b128 v[202:205], v158
	ds_read_b128 v[206:209], v158 offset:1024
	ds_read_b128 v[214:217], v158 offset:2048
	ds_read_b128 v[218:221], v158 offset:3072
	ds_read_b128 v[222:225], v158 offset:4096
	ds_read_b128 v[226:229], v158 offset:5120
	ds_read_b128 v[230:233], v158 offset:6144
	ds_read_b128 v[234:237], v158 offset:7168
	global_load_lds_dwordx4 v[168:169], off
	v_lshl_add_u64 v[168:169], s[40:41], 0, v[136:137]
	s_add_i32 m0, s63, 0xe000
	s_nop 0
	global_load_lds_dwordx4 v[168:169], off
	s_waitcnt vmcnt(8)
	s_waitcnt lgkmcnt(0)
	s_setprio 1
	s_barrier
	v_mfma_f32_16x16x32_bf16 v[126:129], v[152:155], v[202:205], v[126:129]
	v_mfma_f32_16x16x32_bf16 v[122:125], v[164:167], v[202:205], v[122:125]
	v_mfma_f32_16x16x32_bf16 v[110:113], v[152:155], v[214:217], v[110:113]
	v_mfma_f32_16x16x32_bf16 v[106:109], v[164:167], v[214:217], v[106:109]
	v_mfma_f32_16x16x32_bf16 v[94:97], v[152:155], v[222:225], v[94:97]
	v_mfma_f32_16x16x32_bf16 v[90:93], v[164:167], v[222:225], v[90:93]
	v_mfma_f32_16x16x32_bf16 v[78:81], v[152:155], v[230:233], v[78:81]
	v_mfma_f32_16x16x32_bf16 v[74:77], v[164:167], v[230:233], v[74:77]
	v_mfma_f32_16x16x32_bf16 v[126:129], v[160:163], v[206:209], v[126:129]
	v_mfma_f32_16x16x32_bf16 v[122:125], v[182:185], v[206:209], v[122:125]
	v_mfma_f32_16x16x32_bf16 v[110:113], v[160:163], v[218:221], v[110:113]
	v_mfma_f32_16x16x32_bf16 v[106:109], v[182:185], v[218:221], v[106:109]
	v_mfma_f32_16x16x32_bf16 v[94:97], v[160:163], v[226:229], v[94:97]
	v_mfma_f32_16x16x32_bf16 v[90:93], v[182:185], v[226:229], v[90:93]
	v_mfma_f32_16x16x32_bf16 v[78:81], v[160:163], v[234:237], v[78:81]
	v_mfma_f32_16x16x32_bf16 v[74:77], v[182:185], v[234:237], v[74:77]
	s_setprio 0
	s_setprio 1
	v_mfma_f32_16x16x32_bf16 v[118:121], v[186:189], v[202:205], v[118:121]
	v_mfma_f32_16x16x32_bf16 v[114:117], v[194:197], v[202:205], v[114:117]
	v_mfma_f32_16x16x32_bf16 v[102:105], v[186:189], v[214:217], v[102:105]
	v_mfma_f32_16x16x32_bf16 v[98:101], v[194:197], v[214:217], v[98:101]
	v_mfma_f32_16x16x32_bf16 v[86:89], v[186:189], v[222:225], v[86:89]
	v_mfma_f32_16x16x32_bf16 v[82:85], v[194:197], v[222:225], v[82:85]
	v_mfma_f32_16x16x32_bf16 v[70:73], v[186:189], v[230:233], v[70:73]
	v_mfma_f32_16x16x32_bf16 v[66:69], v[194:197], v[230:233], v[66:69]
	v_mfma_f32_16x16x32_bf16 v[118:121], v[190:193], v[206:209], v[118:121]
	v_mfma_f32_16x16x32_bf16 v[114:117], v[198:201], v[206:209], v[114:117]
	v_mfma_f32_16x16x32_bf16 v[102:105], v[190:193], v[218:221], v[102:105]
	v_mfma_f32_16x16x32_bf16 v[98:101], v[198:201], v[218:221], v[98:101]
	v_mfma_f32_16x16x32_bf16 v[86:89], v[190:193], v[226:229], v[86:89]
	v_mfma_f32_16x16x32_bf16 v[82:85], v[198:201], v[226:229], v[82:85]
	v_mfma_f32_16x16x32_bf16 v[70:73], v[190:193], v[234:237], v[70:73]
	v_mfma_f32_16x16x32_bf16 v[66:69], v[198:201], v[234:237], v[66:69]
	s_setprio 0
	s_barrier
	s_add_i32 s75, s75, s62
	v_lshl_add_u64 v[168:169], s[56:57], 0, v[0:1]
	s_mov_b32 m0, s75
	ds_read_b128 v[202:205], v158 offset:16384
	ds_read_b128 v[206:209], v158 offset:17408
	ds_read_b128 v[214:217], v158 offset:18432
	ds_read_b128 v[218:221], v158 offset:19456
	ds_read_b128 v[222:225], v158 offset:20480
	ds_read_b128 v[226:229], v158 offset:21504
	ds_read_b128 v[230:233], v158 offset:22528
	ds_read_b128 v[234:237], v158 offset:23552
	global_load_lds_dwordx4 v[168:169], off
	s_add_i32 m0, s75, 0x2000
	s_add_u32 s76, s56, 0x80000
	v_lshl_add_u64 v[238:239], s[56:57], 0, v[130:131]
	s_addc_u32 s77, s57, 0
	s_add_i32 s75, s78, s62
	global_load_lds_dwordx4 v[238:239], off
	v_lshl_add_u64 v[240:241], s[76:77], 0, v[0:1]
	s_mov_b32 m0, s75
	v_lshl_add_u64 v[242:243], s[58:59], 0, v[132:133]
	global_load_lds_dwordx4 v[240:241], off
	v_lshl_add_u64 v[240:241], s[76:77], 0, v[130:131]
	s_add_i32 m0, s75, 0x2000
	s_nop 0
	global_load_lds_dwordx4 v[240:241], off
	v_lshl_add_u64 v[240:241], s[58:59], 0, v[134:135]
	s_mov_b32 m0, s63
	s_nop 0
	global_load_lds_dwordx4 v[240:241], off
	s_mov_b32 m0, s64
	s_nop 0
	global_load_lds_dwordx4 v[242:243], off
	s_waitcnt vmcnt(8)
	s_waitcnt lgkmcnt(0)
	s_setprio 1
	s_barrier
; #define PG8_STAGE(bufoff, gbase, voff) do { _Pragma("unroll") for (int _i = 0; _i < 2; ++_i) \
;         __builtin_amdgcn_global_load_lds((const unsigned*)((const char*)(gbase) + (voff)[_i]), (PG8_LAS unsigned*)(lds + (bufoff) + ldsw + _i * 8192), 16, 0, 0); } while (0)
; #define PG8_LDA(dst, b, h) do { _Pragma("unroll") for (int m = 0; m < 4; ++m) _Pragma("unroll") for (int k = 0; k < 2; ++k) dst[m][k] = *(const PG8_LAS bf16x8*)(lds + PG8_SA(b, h) + aoff + m * 2048 + k * 1024); } while (0)
; #define PG8_LDB(dst, b, h) do { _Pragma("unroll") for (int n = 0; n < 2; ++n) _Pragma("unroll") for (int k = 0; k < 2; ++k) dst[n][k] = *(const PG8_LAS bf16x8*)(lds + PG8_SB(b, h) + boff + n * 2048 + k * 1024); } while (0)
; #define PG8_MMA(ai, bj, At, Bt) do { __builtin_amdgcn_s_setprio(1); _Pragma("unroll") for (int m = 0; m < 4; ++m) _Pragma("unroll") for (int n = 0; n < 2; ++n) _Pragma("unroll") for (int k = 0; k < 2; ++k) \
;         acc[ai][bj][m][n] = __builtin_amdgcn_mfma_f32_16x16x32_bf16(Bt[n][k], At[m][k], acc[ai][bj][m][n], 0, 0, 0); __builtin_amdgcn_s_setprio(0); } while (0)
; #define PG8_WAIT_V(n) asm volatile("s_waitcnt vmcnt(" #n ")" ::: "memory")
; #define PG8_WAIT_L(n) asm volatile("s_waitcnt lgkmcnt(" #n ")" ::: "memory")
; #define PG8_BAR __builtin_amdgcn_s_barrier()
; #define PG8_SCHED __builtin_amdgcn_sched_barrier(0)
; template <class Epi, class Sched, bool ALIGN_EPI = false, bool SP2 = false>
; __device__ __forceinline__ void gemm_phase(PG8_LAS unsigned char* lds, const Gemm g, const Sched& S, const Epi& E) {
;     ...
;             PG8_WAIT_V(8); PG8_WAIT_L(0); PG8_BAR; PG8_MMA(1, 0, At, B0); PG8_MMA(1, 1, At, B1); PG8_BAR; PG8_SCHED;
;             PG8_LDB(B0, 1, 0); PG8_LDB(B1, 1, 1); PG8_SCHED; PG8_LDA(At, 1, 0); PG8_STAGE(PG8_SA(0, 1), a2 + hstep, voffA);
;             PG8_WAIT_V(8); PG8_WAIT_L(0); PG8_BAR; PG8_MMA(0, 0, At, B0); PG8_MMA(0, 1, At, B1); PG8_BAR; PG8_SCHED;
	v_mfma_f32_16x16x32_bf16 v[62:65], v[152:155], v[202:205], v[62:65]
	v_mfma_f32_16x16x32_bf16 v[58:61], v[164:167], v[202:205], v[58:61]
	v_mfma_f32_16x16x32_bf16 v[46:49], v[152:155], v[214:217], v[46:49]
	v_mfma_f32_16x16x32_bf16 v[42:45], v[164:167], v[214:217], v[42:45]
	v_mfma_f32_16x16x32_bf16 v[30:33], v[152:155], v[222:225], v[30:33]
	v_mfma_f32_16x16x32_bf16 v[26:29], v[164:167], v[222:225], v[26:29]
	v_mfma_f32_16x16x32_bf16 v[14:17], v[152:155], v[230:233], v[14:17]
	v_mfma_f32_16x16x32_bf16 v[10:13], v[164:167], v[230:233], v[10:13]
	v_mfma_f32_16x16x32_bf16 v[62:65], v[160:163], v[206:209], v[62:65]
	v_mfma_f32_16x16x32_bf16 v[58:61], v[182:185], v[206:209], v[58:61]
	v_mfma_f32_16x16x32_bf16 v[46:49], v[160:163], v[218:221], v[46:49]
	v_mfma_f32_16x16x32_bf16 v[42:45], v[182:185], v[218:221], v[42:45]
	v_mfma_f32_16x16x32_bf16 v[30:33], v[160:163], v[226:229], v[30:33]
	v_mfma_f32_16x16x32_bf16 v[26:29], v[182:185], v[226:229], v[26:29]
	v_mfma_f32_16x16x32_bf16 v[14:17], v[160:163], v[234:237], v[14:17]
	v_mfma_f32_16x16x32_bf16 v[10:13], v[182:185], v[234:237], v[10:13]
	s_setprio 0
	s_setprio 1
	v_mfma_f32_16x16x32_bf16 v[54:57], v[186:189], v[202:205], v[54:57]
	v_mfma_f32_16x16x32_bf16 v[50:53], v[194:197], v[202:205], v[50:53]
	v_mfma_f32_16x16x32_bf16 v[38:41], v[186:189], v[214:217], v[38:41]
	v_mfma_f32_16x16x32_bf16 v[34:37], v[194:197], v[214:217], v[34:37]
	v_mfma_f32_16x16x32_bf16 v[22:25], v[186:189], v[222:225], v[22:25]
	v_mfma_f32_16x16x32_bf16 v[18:21], v[194:197], v[222:225], v[18:21]
	v_mfma_f32_16x16x32_bf16 v[6:9], v[186:189], v[230:233], v[6:9]
	v_mfma_f32_16x16x32_bf16 v[2:5], v[194:197], v[230:233], v[2:5]
	v_mfma_f32_16x16x32_bf16 v[54:57], v[190:193], v[206:209], v[54:57]
	v_mfma_f32_16x16x32_bf16 v[50:53], v[198:201], v[206:209], v[50:53]
	v_mfma_f32_16x16x32_bf16 v[38:41], v[190:193], v[218:221], v[38:41]
	v_mfma_f32_16x16x32_bf16 v[34:37], v[198:201], v[218:221], v[34:37]
	v_mfma_f32_16x16x32_bf16 v[22:25], v[190:193], v[226:229], v[22:25]
	v_mfma_f32_16x16x32_bf16 v[18:21], v[198:201], v[226:229], v[18:21]
	v_mfma_f32_16x16x32_bf16 v[6:9], v[190:193], v[234:237], v[6:9]
	v_mfma_f32_16x16x32_bf16 v[2:5], v[198:201], v[234:237], v[2:5]
	s_setprio 0
	s_barrier
	s_add_i32 s75, 0, 0x18000
	v_add_u32_e32 v142, s75, v156
	s_add_i32 s76, 0, 0x1c000
	ds_read_b128 v[152:155], v142
	ds_read_b128 v[160:163], v142 offset:1024
	ds_read_b128 v[164:167], v142 offset:2048
	ds_read_b128 v[182:185], v142 offset:3072
	v_add_u32_e32 v142, s76, v156
	ds_read_b128 v[186:189], v142
	ds_read_b128 v[190:193], v142 offset:1024
	ds_read_b128 v[194:197], v142 offset:2048
	ds_read_b128 v[198:201], v142 offset:3072
	s_add_u32 s58, s58, 0x80000
	s_addc_u32 s59, s59, 0
	s_mov_b32 m0, s65
	v_lshl_add_u64 v[244:245], s[58:59], 0, v[134:135]
	ds_read_b128 v[202:205], v158 offset:32768
	ds_read_b128 v[206:209], v158 offset:33792
	ds_read_b128 v[214:217], v158 offset:34816
	ds_read_b128 v[218:221], v158 offset:35840
	ds_read_b128 v[222:225], v158 offset:36864
	ds_read_b128 v[226:229], v158 offset:37888
	ds_read_b128 v[230:233], v158 offset:38912
	ds_read_b128 v[234:237], v158 offset:39936
	global_load_lds_dwordx4 v[244:245], off
	v_lshl_add_u64 v[244:245], s[58:59], 0, v[132:133]
	s_mov_b32 m0, s66
	s_nop 0
	global_load_lds_dwordx4 v[244:245], off
	s_waitcnt vmcnt(8)
	s_waitcnt lgkmcnt(0)
	s_setprio 1
	s_barrier
	v_mfma_f32_16x16x32_bf16 v[126:129], v[152:155], v[202:205], v[126:129]
	v_mfma_f32_16x16x32_bf16 v[122:125], v[164:167], v[202:205], v[122:125]
	v_mfma_f32_16x16x32_bf16 v[110:113], v[152:155], v[214:217], v[110:113]
	v_mfma_f32_16x16x32_bf16 v[106:109], v[164:167], v[214:217], v[106:109]
	v_mfma_f32_16x16x32_bf16 v[94:97], v[152:155], v[222:225], v[94:97]
	v_mfma_f32_16x16x32_bf16 v[90:93], v[164:167], v[222:225], v[90:93]
	v_mfma_f32_16x16x32_bf16 v[78:81], v[152:155], v[230:233], v[78:81]
	v_mfma_f32_16x16x32_bf16 v[74:77], v[164:167], v[230:233], v[74:77]
	v_mfma_f32_16x16x32_bf16 v[126:129], v[160:163], v[206:209], v[126:129]
	v_mfma_f32_16x16x32_bf16 v[122:125], v[182:185], v[206:209], v[122:125]
	v_mfma_f32_16x16x32_bf16 v[110:113], v[160:163], v[218:221], v[110:113]
	v_mfma_f32_16x16x32_bf16 v[106:109], v[182:185], v[218:221], v[106:109]
	v_mfma_f32_16x16x32_bf16 v[94:97], v[160:163], v[226:229], v[94:97]
	v_mfma_f32_16x16x32_bf16 v[90:93], v[182:185], v[226:229], v[90:93]
	v_mfma_f32_16x16x32_bf16 v[78:81], v[160:163], v[234:237], v[78:81]
	v_mfma_f32_16x16x32_bf16 v[74:77], v[182:185], v[234:237], v[74:77]
	s_setprio 0
	s_setprio 1
	v_mfma_f32_16x16x32_bf16 v[118:121], v[186:189], v[202:205], v[118:121]
	v_mfma_f32_16x16x32_bf16 v[114:117], v[194:197], v[202:205], v[114:117]
	v_mfma_f32_16x16x32_bf16 v[102:105], v[186:189], v[214:217], v[102:105]
	v_mfma_f32_16x16x32_bf16 v[98:101], v[194:197], v[214:217], v[98:101]
	v_mfma_f32_16x16x32_bf16 v[86:89], v[186:189], v[222:225], v[86:89]
	v_mfma_f32_16x16x32_bf16 v[82:85], v[194:197], v[222:225], v[82:85]
	v_mfma_f32_16x16x32_bf16 v[70:73], v[186:189], v[230:233], v[70:73]
	v_mfma_f32_16x16x32_bf16 v[66:69], v[194:197], v[230:233], v[66:69]
	v_mfma_f32_16x16x32_bf16 v[118:121], v[190:193], v[206:209], v[118:121]
	v_mfma_f32_16x16x32_bf16 v[114:117], v[198:201], v[206:209], v[114:117]
	v_mfma_f32_16x16x32_bf16 v[102:105], v[190:193], v[218:221], v[102:105]
	v_mfma_f32_16x16x32_bf16 v[98:101], v[198:201], v[218:221], v[98:101]
	v_mfma_f32_16x16x32_bf16 v[86:89], v[190:193], v[226:229], v[86:89]
	v_mfma_f32_16x16x32_bf16 v[82:85], v[198:201], v[226:229], v[82:85]
	v_mfma_f32_16x16x32_bf16 v[70:73], v[190:193], v[234:237], v[70:73]
	v_mfma_f32_16x16x32_bf16 v[66:69], v[198:201], v[234:237], v[66:69]
	s_setprio 0
	s_barrier
; #define PG8_STAGE(bufoff, gbase, voff) do { _Pragma("unroll") for (int _i = 0; _i < 2; ++_i) \
;         __builtin_amdgcn_global_load_lds((const unsigned*)((const char*)(gbase) + (voff)[_i]), (PG8_LAS unsigned*)(lds + (bufoff) + ldsw + _i * 8192), 16, 0, 0); } while (0)
; #define PG8_LDA(dst, b, h) do { _Pragma("unroll") for (int m = 0; m < 4; ++m) _Pragma("unroll") for (int k = 0; k < 2; ++k) dst[m][k] = *(const PG8_LAS bf16x8*)(lds + PG8_SA(b, h) + aoff + m * 2048 + k * 1024); } while (0)
; #define PG8_MMA(ai, bj, At, Bt) do { __builtin_amdgcn_s_setprio(1); _Pragma("unroll") for (int m = 0; m < 4; ++m) _Pragma("unroll") for (int n = 0; n < 2; ++n) _Pragma("unroll") for (int k = 0; k < 2; ++k) \
;         acc[ai][bj][m][n] = __builtin_amdgcn_mfma_f32_16x16x32_bf16(Bt[n][k], At[m][k], acc[ai][bj][m][n], 0, 0, 0); __builtin_amdgcn_s_setprio(0); } while (0)
; #define PG8_WAIT_V(n) asm volatile("s_waitcnt vmcnt(" #n ")" ::: "memory")
; #define PG8_WAIT_L(n) asm volatile("s_waitcnt lgkmcnt(" #n ")" ::: "memory")
; #define PG8_BAR __builtin_amdgcn_s_barrier()
; #define PG8_SCHED __builtin_amdgcn_sched_barrier(0)
; template <class Epi, class Sched, bool ALIGN_EPI = false, bool SP2 = false>
; __device__ __forceinline__ void gemm_phase(PG8_LAS unsigned char* lds, const Gemm g, const Sched& S, const Epi& E) {
;     ...
;         for (int t = 0; t < nt; t += 2) {
;     ...
;             PG8_LDA(At, 1, 1); PG8_STAGE(PG8_SB(1, 0), b3, voffB); PG8_STAGE(PG8_SB(1, 1), b3 + hstep, voffB); PG8_STAGE(PG8_SA(1, 0), a3, voffA);
;             PG8_WAIT_V(8); PG8_WAIT_L(0); PG8_BAR; PG8_MMA(1, 0, At, B0); PG8_MMA(1, 1, At, B1); PG8_BAR; PG8_SCHED;
	s_add_i32 s58, s75, s62
	v_lshl_add_u64 v[168:169], v[168:169], 0, s[34:35]
	s_mov_b32 m0, s58
	ds_read_b128 v[202:205], v158 offset:49152
	ds_read_b128 v[206:209], v158 offset:50176
	ds_read_b128 v[214:217], v158 offset:51200
	ds_read_b128 v[218:221], v158 offset:52224
	ds_read_b128 v[222:225], v158 offset:53248
	ds_read_b128 v[226:229], v158 offset:54272
	ds_read_b128 v[230:233], v158 offset:55296
	ds_read_b128 v[234:237], v158 offset:56320
	global_load_lds_dwordx4 v[168:169], off
	s_add_i32 m0, s58, 0x2000
	s_add_u32 s56, s56, 0x80080
	v_lshl_add_u64 v[168:169], v[238:239], 0, s[34:35]
	s_addc_u32 s57, s57, 0
	s_add_i32 s58, s76, s62
	global_load_lds_dwordx4 v[168:169], off
	v_lshl_add_u64 v[168:169], s[56:57], 0, v[0:1]
	s_mov_b32 m0, s58
	s_nop 0
	global_load_lds_dwordx4 v[168:169], off
	v_lshl_add_u64 v[168:169], s[56:57], 0, v[130:131]
	s_add_i32 m0, s58, 0x2000
	s_nop 0
	global_load_lds_dwordx4 v[168:169], off
	v_lshl_add_u64 v[168:169], v[240:241], 0, s[34:35]
	s_mov_b32 m0, s67
	s_nop 0
	global_load_lds_dwordx4 v[168:169], off
	v_lshl_add_u64 v[168:169], v[242:243], 0, s[34:35]
	s_mov_b32 m0, s68
	s_nop 0
	global_load_lds_dwordx4 v[168:169], off
	s_waitcnt vmcnt(8)
	s_waitcnt lgkmcnt(0)
	s_setprio 1
	s_barrier
	v_mfma_f32_16x16x32_bf16 v[62:65], v[152:155], v[202:205], v[62:65]
	v_mfma_f32_16x16x32_bf16 v[58:61], v[164:167], v[202:205], v[58:61]
	v_mfma_f32_16x16x32_bf16 v[46:49], v[152:155], v[214:217], v[46:49]
	v_mfma_f32_16x16x32_bf16 v[42:45], v[164:167], v[214:217], v[42:45]
	v_mfma_f32_16x16x32_bf16 v[30:33], v[152:155], v[222:225], v[30:33]
	v_mfma_f32_16x16x32_bf16 v[26:29], v[164:167], v[222:225], v[26:29]
	v_mfma_f32_16x16x32_bf16 v[14:17], v[152:155], v[230:233], v[14:17]
	v_mfma_f32_16x16x32_bf16 v[10:13], v[164:167], v[230:233], v[10:13]
	v_mfma_f32_16x16x32_bf16 v[62:65], v[160:163], v[206:209], v[62:65]
	v_mfma_f32_16x16x32_bf16 v[58:61], v[182:185], v[206:209], v[58:61]
	v_mfma_f32_16x16x32_bf16 v[46:49], v[160:163], v[218:221], v[46:49]
	v_mfma_f32_16x16x32_bf16 v[42:45], v[182:185], v[218:221], v[42:45]
	v_mfma_f32_16x16x32_bf16 v[30:33], v[160:163], v[226:229], v[30:33]
	v_mfma_f32_16x16x32_bf16 v[26:29], v[182:185], v[226:229], v[26:29]
	v_mfma_f32_16x16x32_bf16 v[14:17], v[160:163], v[234:237], v[14:17]
	v_mfma_f32_16x16x32_bf16 v[10:13], v[182:185], v[234:237], v[10:13]
	s_setprio 0
	s_setprio 1
	v_mfma_f32_16x16x32_bf16 v[54:57], v[186:189], v[202:205], v[54:57]
	v_mfma_f32_16x16x32_bf16 v[50:53], v[194:197], v[202:205], v[50:53]
	v_mfma_f32_16x16x32_bf16 v[38:41], v[186:189], v[214:217], v[38:41]
	v_mfma_f32_16x16x32_bf16 v[34:37], v[194:197], v[214:217], v[34:37]
	v_mfma_f32_16x16x32_bf16 v[22:25], v[186:189], v[222:225], v[22:25]
	v_mfma_f32_16x16x32_bf16 v[18:21], v[194:197], v[222:225], v[18:21]
	v_mfma_f32_16x16x32_bf16 v[6:9], v[186:189], v[230:233], v[6:9]
	v_mfma_f32_16x16x32_bf16 v[2:5], v[194:197], v[230:233], v[2:5]
	v_mfma_f32_16x16x32_bf16 v[54:57], v[190:193], v[206:209], v[54:57]
	v_mfma_f32_16x16x32_bf16 v[50:53], v[198:201], v[206:209], v[50:53]
	v_mfma_f32_16x16x32_bf16 v[38:41], v[190:193], v[218:221], v[38:41]
	v_mfma_f32_16x16x32_bf16 v[34:37], v[198:201], v[218:221], v[34:37]
	v_mfma_f32_16x16x32_bf16 v[22:25], v[190:193], v[226:229], v[22:25]
	v_mfma_f32_16x16x32_bf16 v[18:21], v[198:201], v[226:229], v[18:21]
	v_mfma_f32_16x16x32_bf16 v[6:9], v[190:193], v[234:237], v[6:9]
	v_mfma_f32_16x16x32_bf16 v[2:5], v[198:201], v[234:237], v[2:5]
	s_setprio 0
	s_add_i32 s74, s74, 2
	s_add_u32 s72, s72, 0x100
	s_addc_u32 s73, s73, 0
	s_add_u32 s40, s40, 0x100
	s_addc_u32 s41, s41, 0
	s_cmp_gt_u32 s74, 29
	s_cbranch_scc0 .Lg1_head_bar
	s_barrier
	s_and_b64 vcc, exec, s[44:45]
	s_cbranch_vccz .LBB0_421
	s_barrier
